# nsa: block-importance accumulation via LDS float atomic add instead of read-modify-write (on top of v16)
# baseline (speedup 1.0000x reference)
.LBB0_1436:
	v_sub_f32_e32 v80, v80, v109
	v_sub_f32_e32 v81, v81, v109
	v_sub_f32_e32 v82, v82, v109
	v_sub_f32_e32 v83, v83, v109
	v_exp_f32_e32 v80, v80
	v_exp_f32_e32 v81, v81
	v_exp_f32_e32 v82, v82
	v_exp_f32_e32 v83, v83
	v_pk_mul_f32 v[80:81], v[96:97], v[80:81]
	v_pk_mul_f32 v[82:83], v[96:97], v[82:83]
	v_add_f32_e32 v111, v80, v81
	v_mul_f32_e32 v112, 0.5, v83
	v_fma_f32 v113, 0.5, v83, v82
	v_add_f32_e32 v111, v111, v113
	v_mov_b32_dpp v112, v112 quad_perm:[1,0,3,2] row_mask:0xf bank_mask:0xf bound_ctrl:1
	v_fmac_f32_e32 v112, 0.5, v83
	v_add_f32_dpp v114, v111, v111 quad_perm:[1,0,3,2] row_mask:0xf bank_mask:0xf bound_ctrl:1
	v_add_u32_e32 v111, s18, v110
	v_mov_b32_dpp v113, v112 quad_perm:[2,3,0,1] row_mask:0xf bank_mask:0xf bound_ctrl:1
	v_mov_b32_dpp v115, v114 quad_perm:[2,3,0,1] row_mask:0xf bank_mask:0xf bound_ctrl:1
	s_and_saveexec_b64 s[14:15], s[10:11]
	s_cbranch_execz .LBB0_1438
	v_add_u32_e32 v128, 0x12000, v111
	v_add_f32_e32 v114, v114, v115
	ds_add_f32 v128, v114
.LBB0_1438:
	s_or_b64 exec, exec, s[14:15]
	s_and_saveexec_b64 s[14:15], s[10:11]
	s_cbranch_execz .LBB0_1440
	v_add_u32_e32 v114, 0x12004, v111
	v_add_f32_e32 v112, v112, v113
	ds_add_f32 v114, v112
.LBB0_1440:
	s_or_b64 exec, exec, s[14:15]
	v_sub_f32_e32 v76, v76, v109
	v_sub_f32_e32 v77, v77, v109
	v_sub_f32_e32 v78, v78, v109
	v_sub_f32_e32 v79, v79, v109
	v_exp_f32_e32 v76, v76
	v_exp_f32_e32 v77, v77
	v_exp_f32_e32 v78, v78
	v_exp_f32_e32 v79, v79
	v_pk_mul_f32 v[76:77], v[96:97], v[76:77]
	v_pk_mul_f32 v[78:79], v[96:97], v[78:79]
	v_add_f32_e32 v112, v76, v77
	v_fma_f32 v114, 0.5, v79, v78
	v_mul_f32_e32 v113, 0.5, v79
	v_add_f32_e32 v112, v112, v114
	s_nop 1
	v_add_f32_dpp v114, v112, v112 quad_perm:[1,0,3,2] row_mask:0xf bank_mask:0xf bound_ctrl:1
	v_mov_b32_dpp v112, v113 quad_perm:[1,0,3,2] row_mask:0xf bank_mask:0xf bound_ctrl:1
	v_fmac_f32_e32 v112, 0.5, v79
	v_mov_b32_dpp v115, v114 quad_perm:[2,3,0,1] row_mask:0xf bank_mask:0xf bound_ctrl:1
	s_nop 0
	v_mov_b32_dpp v113, v112 quad_perm:[2,3,0,1] row_mask:0xf bank_mask:0xf bound_ctrl:1
	s_and_saveexec_b64 s[14:15], s[10:11]
	s_cbranch_execz .LBB0_1442
	v_add_u32_e32 v128, 0x12010, v111
	v_add_f32_e32 v114, v114, v115
	ds_add_f32 v128, v114
.LBB0_1442:
	s_or_b64 exec, exec, s[14:15]
	s_and_saveexec_b64 s[14:15], s[10:11]
	s_cbranch_execz .LBB0_1444
	v_add_u32_e32 v114, 0x12014, v111
	v_add_f32_e32 v112, v112, v113
	ds_add_f32 v114, v112
.LBB0_1444:
	s_or_b64 exec, exec, s[14:15]
	v_sub_f32_e32 v72, v72, v109
	v_sub_f32_e32 v73, v73, v109
	v_sub_f32_e32 v74, v74, v109
	v_sub_f32_e32 v75, v75, v109
	v_exp_f32_e32 v72, v72
	v_exp_f32_e32 v73, v73
	v_exp_f32_e32 v74, v74
	v_exp_f32_e32 v75, v75
	v_pk_mul_f32 v[72:73], v[96:97], v[72:73]
	v_pk_mul_f32 v[74:75], v[96:97], v[74:75]
	v_add_f32_e32 v112, v72, v73
	v_fma_f32 v114, 0.5, v75, v74
	v_mul_f32_e32 v113, 0.5, v75
	v_add_f32_e32 v112, v112, v114
	s_nop 1
	v_add_f32_dpp v114, v112, v112 quad_perm:[1,0,3,2] row_mask:0xf bank_mask:0xf bound_ctrl:1
	v_mov_b32_dpp v112, v113 quad_perm:[1,0,3,2] row_mask:0xf bank_mask:0xf bound_ctrl:1
	v_fmac_f32_e32 v112, 0.5, v75
	v_mov_b32_dpp v115, v114 quad_perm:[2,3,0,1] row_mask:0xf bank_mask:0xf bound_ctrl:1
	s_nop 0
	v_mov_b32_dpp v113, v112 quad_perm:[2,3,0,1] row_mask:0xf bank_mask:0xf bound_ctrl:1
	s_and_saveexec_b64 s[14:15], s[10:11]
	s_cbranch_execz .LBB0_1446
	v_add_u32_e32 v128, 0x12020, v111
	v_add_f32_e32 v114, v114, v115
	ds_add_f32 v128, v114
.LBB0_1446:
	s_or_b64 exec, exec, s[14:15]
	s_and_saveexec_b64 s[14:15], s[10:11]
	s_cbranch_execz .LBB0_1448
	v_add_u32_e32 v114, 0x12024, v111
	v_add_f32_e32 v112, v112, v113
	ds_add_f32 v114, v112
.LBB0_1448:
	s_or_b64 exec, exec, s[14:15]
	v_sub_f32_e32 v68, v68, v109
	v_sub_f32_e32 v69, v69, v109
	v_sub_f32_e32 v70, v70, v109
	v_sub_f32_e32 v71, v71, v109
	v_exp_f32_e32 v68, v68
	v_exp_f32_e32 v69, v69
	v_exp_f32_e32 v70, v70
	v_exp_f32_e32 v71, v71
	v_pk_mul_f32 v[68:69], v[96:97], v[68:69]
	v_pk_mul_f32 v[70:71], v[96:97], v[70:71]
	v_add_f32_e32 v112, v68, v69
	v_fma_f32 v114, 0.5, v71, v70
	v_mul_f32_e32 v113, 0.5, v71
	v_add_f32_e32 v112, v112, v114
	s_nop 1
	v_add_f32_dpp v114, v112, v112 quad_perm:[1,0,3,2] row_mask:0xf bank_mask:0xf bound_ctrl:1
	v_mov_b32_dpp v112, v113 quad_perm:[1,0,3,2] row_mask:0xf bank_mask:0xf bound_ctrl:1
	v_fmac_f32_e32 v112, 0.5, v71
	v_mov_b32_dpp v115, v114 quad_perm:[2,3,0,1] row_mask:0xf bank_mask:0xf bound_ctrl:1
	s_nop 0
	v_mov_b32_dpp v113, v112 quad_perm:[2,3,0,1] row_mask:0xf bank_mask:0xf bound_ctrl:1
	s_and_saveexec_b64 s[14:15], s[10:11]
	s_cbranch_execz .LBB0_1450
	v_add_u32_e32 v128, 0x12030, v111
	v_add_f32_e32 v114, v114, v115
	ds_add_f32 v128, v114
.LBB0_1450:
	s_or_b64 exec, exec, s[14:15]
	s_movk_i32 s14, 0x7f
	v_cmp_gt_u32_e32 vcc, s14, v87
	s_and_b64 s[68:69], s[10:11], vcc
	s_and_saveexec_b64 s[14:15], s[68:69]
	s_cbranch_execz .LBB0_1452
	v_add_u32_e32 v111, 0x12034, v111
	v_add_f32_e32 v112, v112, v113
	ds_add_f32 v111, v112
